# st4: conv+pool token ops moved to WGs 128-255 (WGs 64-127 carry 2 attention units per wave)
# speedup vs baseline: 1.0578x; 1.0021x over previous
.LBB0_379:
	s_cmp_eq_u32 s41, 4
	v_readlane_b32 s31, v253, 37
	s_mul_i32 s34, s33, 24
	s_mov_b32 s35, 0x800000
	s_cbranch_scc0 .LBB0_471
	v_mov_b32_e32 v148, v244
	v_readlane_b32 s0, v253, 33
	s_cmp_lt_i32 s52, s0
	v_readfirstlane_b32 s22, v148
	s_cbranch_scc1 .LBB0_471
	v_readlane_b32 s0, v253, 47
	s_nop 1
	v_mov_b32_e32 v0, s0
	ds_read_b64 v[0:1], v0
	v_readlane_b32 s0, v253, 33
	s_sub_i32 s23, s52, s0
	v_lshl_add_u32 v149, s23, 9, v148
	s_cmpk_lg_i32 s33, 0x100
	s_cbranch_scc1 .Lcp_keep
	s_add_i32 s4, s52, 0xffffff80
	v_lshl_add_u32 v149, s4, 9, v148
	s_cmp_lt_i32 s4, 0
	s_cbranch_scc0 .Lcp_keep
	v_mov_b32_e32 v149, s95
.Lcp_keep:
	v_cmp_gt_i32_e32 vcc, s95, v149
	s_waitcnt lgkmcnt(0)
	v_readfirstlane_b32 s0, v1
	v_readfirstlane_b32 s1, v0
	s_and_saveexec_b64 s[4:5], vcc
	s_cbranch_execz .LBB0_464
	v_readlane_b32 s6, v254, 57
	v_readlane_b32 s7, v254, 58
	s_mul_hi_i32 s7, s6, 0xc00
	s_mulk_i32 s6, 0xc00
	s_add_u32 s6, s1, s6
	s_addc_u32 s7, s0, s7
	v_lshlrev_b32_e32 v150, 3, v149
	s_mov_b64 s[8:9], 0
	s_branch .LBB0_385

.LBB0_384:
	s_or_b64 exec, exec, s[0:1]
	v_readlane_b32 s0, v253, 21
	s_cmpk_eq_i32 s33, 0x100
	s_cselect_b32 s0, 0x10000, s0
	s_nop 1
	v_add_u32_e32 v149, s0, v149
	s_mov_b32 s0, 0x1ffff
	v_cmp_lt_i32_e32 vcc, s0, v149
	v_readlane_b32 s0, v253, 34
	s_cmpk_eq_i32 s33, 0x100
	s_cselect_b32 s0, 0x80000, s0
	s_or_b64 s[8:9], vcc, s[8:9]
	s_nop 0
	v_add_u32_e32 v150, s0, v150
	s_andn2_b64 exec, exec, s[8:9]
	s_cbranch_execz .LBB0_464
